# SEAM 6 waits only for the four owners of the row panel (per-panel counter) instead of the 16-workgroup group
# baseline (speedup 1.0000x reference)
.LBB0_629:
	s_cmp_gt_i32 s95, 7
	s_cselect_b64 s[0:1], -1, 0
	s_and_b64 s[4:5], s[4:5], s[0:1]
	s_andn2_b64 vcc, exec, s[4:5]
	s_cbranch_vccnz .LBB0_683
	s_waitcnt vmcnt(0)
	s_waitcnt vmcnt(0)
	s_barrier
	s_mov_b64 s[4:5], exec
	v_readlane_b32 s6, v246, 2
	v_readlane_b32 s7, v246, 3
	s_and_b64 s[6:7], s[4:5], s[6:7]
	s_mov_b64 exec, s[6:7]
	s_cbranch_execz .LBB0_682
	s_and_b32 s6, s2, 7
	s_lshl_b32 s6, s6, 3
	s_bfe_u32 s7, s2, 0x30003
	s_or_b32 s6, s6, s7
	s_lshl_b32 s6, s6, 8
	s_add_u32 s6, s6, 0x9000
	s_add_u32 s6, s92, s6
	s_addc_u32 s7, s93, 0
	s_add_u32 s6, s6, 0x53000
	s_addc_u32 s7, s7, 0
	s_add_u32 s8, s92, 0x54000
	s_addc_u32 s9, s93, 0
	v_mov_b32_e32 v1, 0
	v_mov_b32_e32 v2, 1
	global_atomic_add v1, v2, s[6:7]
	s_mov_b32 s10, 0x400000
	s_movk_i32 s11, 3
	global_atomic_add v1, v2, s[8:9]
	global_load_dword v4, v1, s[8:9] offset:256 sc1
	global_load_dword v3, v1, s[6:7] sc1
	s_waitcnt vmcnt(0)
	v_readfirstlane_b32 s98, v4
	s_cmp_lg_u32 s98, 0
	s_cbranch_scc1 .Lgb6_orig
	v_cmp_lt_u32_e32 vcc, s11, v3
	s_cbranch_vccnz .Lgb6_ok

.LBB0_761:
	s_cmp_gt_i32 s95, 8
	s_cselect_b64 s[0:1], -1, 0
	s_and_b64 s[4:5], s[6:7], s[0:1]
	s_andn2_b64 vcc, exec, s[4:5]
	s_cbranch_vccnz .LBB0_815
	s_waitcnt vmcnt(0)
	s_waitcnt vmcnt(0)
	s_barrier
	s_mov_b64 s[4:5], exec
	v_readlane_b32 s6, v246, 2
	v_readlane_b32 s7, v246, 3
	s_and_b64 s[6:7], s[4:5], s[6:7]
	s_mov_b64 exec, s[6:7]
	s_cbranch_execz .LBB0_814
	s_cmp_lg_u32 s98, 0
	s_cbranch_scc1 .Lgb7_orig
	s_and_b32 s6, s2, 15
	s_lshl_b32 s6, s6, 8
	s_add_u32 s6, s92, s6
	s_addc_u32 s7, s93, 0
	s_add_u32 s6, s6, 0x53000
	s_addc_u32 s7, s7, 0
	s_add_u32 s8, s92, 0x54000
	s_addc_u32 s9, s93, 0
	v_mov_b32_e32 v1, 0
	v_mov_b32_e32 v2, 1
	global_atomic_add v1, v2, s[6:7]
	s_mov_b32 s10, 0x400000
	s_movk_i32 s11, 15

.LBB0_836:
	s_cmp_gt_i32 s95, 9
	s_cselect_b64 s[0:1], -1, 0
	s_and_b64 s[4:5], s[4:5], s[0:1]
	s_andn2_b64 vcc, exec, s[4:5]
	s_cbranch_vccnz .LBB0_890
	s_waitcnt vmcnt(0)
	s_waitcnt vmcnt(0)
	s_barrier
	s_mov_b64 s[4:5], exec
	v_readlane_b32 s6, v246, 2
	v_readlane_b32 s7, v246, 3
	s_and_b64 s[6:7], s[4:5], s[6:7]
	s_mov_b64 exec, s[6:7]
	s_cbranch_execz .LBB0_889
	s_cmp_lg_u32 s98, 0
	s_cbranch_scc1 .Lgb8_orig
	s_and_b32 s6, s2, 15
	s_lshl_b32 s6, s6, 8
	s_add_u32 s6, s92, s6
	s_addc_u32 s7, s93, 0
	s_add_u32 s6, s6, 0x53000
	s_addc_u32 s7, s7, 0
	s_add_u32 s8, s92, 0x54000
	s_addc_u32 s9, s93, 0
	v_mov_b32_e32 v1, 0
	v_mov_b32_e32 v2, 1
	global_atomic_add v1, v2, s[6:7]
	s_mov_b32 s10, 0x400000
	s_movk_i32 s11, 31
